# slot gather in a single batch of 8 loads (st1 reads only the sum halves); plus noinv and permlane-swap shuffles
# baseline (speedup 1.0000x reference)
.LBB0_439:
	s_waitcnt vmcnt(0) lgkmcnt(0)
	s_barrier
	ds_read_b32 v231, v223 offset:10240
	s_and_saveexec_b64 s[18:19], s[10:11]
	s_cbranch_execz .LBB0_441
	v_lshlrev_b64 v[210:211], 6, v[220:221]
	v_lshl_add_u64 v[210:211], s[16:17], 0, v[210:211]
	s_waitcnt lgkmcnt(1)
	global_load_dword v212, v[210:211], off sc1
	global_load_dword v213, v[210:211], off offset:8 sc1
	global_load_dword v214, v[210:211], off offset:16 sc1
	global_load_dword v215, v[210:211], off offset:24 sc1
	global_load_dword v216, v[210:211], off offset:32 sc1
	global_load_dword v217, v[210:211], off offset:40 sc1
	global_load_dword v226, v[210:211], off offset:48 sc1
	global_load_dword v227, v[210:211], off offset:56 sc1
	s_mov_b32 s16, 0xf800000
	s_waitcnt vmcnt(0)
	v_add_f32_e32 v210, 0, v212
	v_add_f32_e32 v210, v210, v213
	v_add_f32_e32 v210, v210, v214
	v_add_f32_e32 v210, v210, v215
	v_add_f32_e32 v210, v210, v216
	v_add_f32_e32 v210, v210, v217
	v_add_f32_e32 v210, v210, v226
	v_add_f32_e32 v210, v210, v227
	v_fmamk_f32 v210, v210, 0x3a000000, v242
	v_cmp_gt_f32_e32 vcc, s16, v210
	v_mul_f32_e32 v212, 0x4f800000, v210
	v_mov_b32_e32 v211, 0
	v_cndmask_b32_e32 v210, v210, v212, vcc
	v_sqrt_f32_e32 v212, v210
	s_nop 0
	v_add_u32_e32 v213, -1, v212
	v_fma_f32 v214, -v213, v212, v210
	v_cmp_ge_f32_e64 s[16:17], 0, v214
	v_add_u32_e32 v214, 1, v212
	s_nop 0
	v_cndmask_b32_e64 v213, v212, v213, s[16:17]
	v_fma_f32 v212, -v214, v212, v210
	v_cmp_lt_f32_e64 s[16:17], 0, v212
	s_nop 1
	v_cndmask_b32_e64 v212, v213, v214, s[16:17]
	v_mul_f32_e32 v213, 0x37800000, v212
	v_cndmask_b32_e32 v212, v212, v213, vcc
	v_cmp_class_f32_e32 vcc, v210, v243
	s_nop 1
	v_cndmask_b32_e32 v210, v212, v210, vcc
	v_div_scale_f32 v212, s[16:17], v210, v210, 1.0
	v_rcp_f32_e32 v213, v212
	s_nop 0
	v_fma_f32 v214, -v212, v213, 1.0
	v_fmac_f32_e32 v213, v214, v213
	v_div_scale_f32 v214, vcc, 1.0, v210, 1.0
	v_mul_f32_e32 v215, v214, v213
	v_fma_f32 v216, -v212, v215, v214
	v_fmac_f32_e32 v215, v216, v213
	v_fma_f32 v212, -v212, v215, v214
	v_div_fmas_f32 v212, v212, v213, v215
	v_div_fixup_f32 v210, v212, v210, 1.0
	v_lshl_add_u32 v212, v236, 3, 0
	ds_write_b64 v212, v[210:211] offset:8192

.LBB0_608:
	s_waitcnt vmcnt(0) lgkmcnt(0)
	s_barrier
	ds_read_b32 v164, v223 offset:10240
	s_and_saveexec_b64 s[8:9], s[10:11]
	s_cbranch_execz .LBB0_610
	s_waitcnt lgkmcnt(1)
	v_lshlrev_b64 v[166:167], 6, v[220:221]
	v_lshl_add_u64 v[166:167], s[6:7], 0, v[166:167]
	global_load_dwordx2 v[168:169], v[166:167], off sc1
	global_load_dwordx2 v[172:173], v[166:167], off offset:8 sc1
	global_load_dwordx2 v[174:175], v[166:167], off offset:16 sc1
	global_load_dwordx2 v[176:177], v[166:167], off offset:24 sc1
	global_load_dwordx2 v[180:181], v[166:167], off offset:32 sc1
	global_load_dwordx2 v[182:183], v[166:167], off offset:40 sc1
	global_load_dwordx2 v[184:185], v[166:167], off offset:48 sc1
	global_load_dwordx2 v[166:167], v[166:167], off offset:56 sc1
	s_mov_b32 s6, 0xf800000
	s_waitcnt vmcnt(0)
	v_add_f32_e32 v165, 0, v168
	v_add_f32_e32 v165, v165, v172
	v_add_f32_e32 v165, v165, v174
	v_add_f32_e32 v165, v165, v176
	v_add_f32_e32 v165, v165, v180
	v_add_f32_e32 v165, v165, v182
	v_add_f32_e32 v165, v165, v184
	v_max3_f32 v169, v169, 0, v173
	v_max3_f32 v169, v169, v175, v177
	v_max3_f32 v172, v169, v181, v183
	v_mov_b32_e32 v169, v185
	v_add_f32_e32 v165, v165, v166
	v_fmamk_f32 v165, v165, 0x3a000000, v242
	v_cmp_gt_f32_e32 vcc, s6, v165
	v_mul_f32_e32 v166, 0x4f800000, v165
	v_max3_f32 v167, v172, v169, v167
	v_cndmask_b32_e32 v165, v165, v166, vcc
	v_sqrt_f32_e32 v166, v165
	s_nop 0
	v_add_u32_e32 v168, -1, v166
	v_fma_f32 v169, -v168, v166, v165
	v_cmp_ge_f32_e64 s[6:7], 0, v169
	v_add_u32_e32 v169, 1, v166
	s_nop 0
	v_cndmask_b32_e64 v168, v166, v168, s[6:7]
	v_fma_f32 v166, -v169, v166, v165
	v_cmp_lt_f32_e64 s[6:7], 0, v166
	s_nop 1
	v_cndmask_b32_e64 v166, v168, v169, s[6:7]
	v_mul_f32_e32 v168, 0x37800000, v166
	v_cndmask_b32_e32 v166, v166, v168, vcc
	v_cmp_class_f32_e32 vcc, v165, v243
	s_nop 1
	v_cndmask_b32_e32 v165, v166, v165, vcc
	v_div_scale_f32 v166, s[6:7], v165, v165, 1.0
	v_rcp_f32_e32 v168, v166
	s_nop 0
	v_fma_f32 v169, -v166, v168, 1.0
	v_fmac_f32_e32 v168, v169, v168
	v_div_scale_f32 v169, vcc, 1.0, v165, 1.0
	v_mul_f32_e32 v172, v169, v168
	v_fma_f32 v173, -v166, v172, v169
	v_fmac_f32_e32 v172, v173, v168
	v_fma_f32 v166, -v166, v172, v169
	v_div_fmas_f32 v166, v166, v168, v172
	v_div_fixup_f32 v166, v166, v165, 1.0
	v_lshl_add_u32 v165, v236, 3, 0
	ds_write_b64 v165, v[166:167] offset:8192

.LBB0_1234:
	s_waitcnt vmcnt(0) lgkmcnt(0)
	s_barrier
	ds_read_b32 v231, v223 offset:10240
	s_and_saveexec_b64 s[16:17], s[8:9]
	s_cbranch_execz .LBB0_1236
	v_lshlrev_b64 v[210:211], 6, v[220:221]
	v_lshl_add_u64 v[210:211], s[14:15], 0, v[210:211]
	s_waitcnt lgkmcnt(1)
	global_load_dword v212, v[210:211], off sc1
	global_load_dword v213, v[210:211], off offset:8 sc1
	global_load_dword v214, v[210:211], off offset:16 sc1
	global_load_dword v215, v[210:211], off offset:24 sc1
	global_load_dword v216, v[210:211], off offset:32 sc1
	global_load_dword v217, v[210:211], off offset:40 sc1
	global_load_dword v226, v[210:211], off offset:48 sc1
	global_load_dword v227, v[210:211], off offset:56 sc1
	s_mov_b32 s14, 0xf800000
	s_waitcnt vmcnt(0)
	v_add_f32_e32 v210, 0, v212
	v_add_f32_e32 v210, v210, v213
	v_add_f32_e32 v210, v210, v214
	v_add_f32_e32 v210, v210, v215
	v_add_f32_e32 v210, v210, v216
	v_add_f32_e32 v210, v210, v217
	v_add_f32_e32 v210, v210, v226
	v_add_f32_e32 v210, v210, v227
	v_fmamk_f32 v210, v210, 0x3a000000, v242
	v_cmp_gt_f32_e32 vcc, s14, v210
	v_mul_f32_e32 v212, 0x4f800000, v210
	v_mov_b32_e32 v211, 0
	v_cndmask_b32_e32 v210, v210, v212, vcc
	v_sqrt_f32_e32 v212, v210
	s_nop 0
	v_add_u32_e32 v213, -1, v212
	v_fma_f32 v214, -v213, v212, v210
	v_cmp_ge_f32_e64 s[14:15], 0, v214
	v_add_u32_e32 v214, 1, v212
	s_nop 0
	v_cndmask_b32_e64 v213, v212, v213, s[14:15]
	v_fma_f32 v212, -v214, v212, v210
	v_cmp_lt_f32_e64 s[14:15], 0, v212
	s_nop 1
	v_cndmask_b32_e64 v212, v213, v214, s[14:15]
	v_mul_f32_e32 v213, 0x37800000, v212
	v_cndmask_b32_e32 v212, v212, v213, vcc
	v_cmp_class_f32_e32 vcc, v210, v243
	s_nop 1
	v_cndmask_b32_e32 v210, v212, v210, vcc
	v_div_scale_f32 v212, s[14:15], v210, v210, 1.0
	v_rcp_f32_e32 v213, v212
	s_nop 0
	v_fma_f32 v214, -v212, v213, 1.0
	v_fmac_f32_e32 v213, v214, v213
	v_div_scale_f32 v214, vcc, 1.0, v210, 1.0
	v_mul_f32_e32 v215, v214, v213
	v_fma_f32 v216, -v212, v215, v214
	v_fmac_f32_e32 v215, v216, v213
	v_fma_f32 v212, -v212, v215, v214
	v_div_fmas_f32 v212, v212, v213, v215
	v_div_fixup_f32 v210, v212, v210, 1.0
	v_lshl_add_u32 v212, v236, 3, 0
	ds_write_b64 v212, v[210:211] offset:8192

.LBB0_1403:
	s_waitcnt vmcnt(0) lgkmcnt(0)
	s_barrier
	ds_read_b32 v166, v223 offset:10240
	s_and_saveexec_b64 s[6:7], s[8:9]
	s_cbranch_execz .LBB0_1405
	s_waitcnt lgkmcnt(2)
	v_lshlrev_b64 v[164:165], 6, v[220:221]
	v_lshl_add_u64 v[164:165], s[4:5], 0, v[164:165]
	global_load_dwordx2 v[168:169], v[164:165], off sc1
	global_load_dwordx2 v[172:173], v[164:165], off offset:8 sc1
	global_load_dwordx2 v[174:175], v[164:165], off offset:16 sc1
	global_load_dwordx2 v[176:177], v[164:165], off offset:24 sc1
	global_load_dwordx2 v[180:181], v[164:165], off offset:32 sc1
	global_load_dwordx2 v[182:183], v[164:165], off offset:40 sc1
	global_load_dwordx2 v[184:185], v[164:165], off offset:48 sc1
	global_load_dwordx2 v[164:165], v[164:165], off offset:56 sc1
	s_mov_b32 s4, 0xf800000
	s_waitcnt vmcnt(0) lgkmcnt(1)
	v_add_f32_e32 v167, 0, v168
	v_add_f32_e32 v167, v167, v172
	v_add_f32_e32 v167, v167, v174
	v_add_f32_e32 v167, v167, v176
	v_add_f32_e32 v167, v167, v180
	v_add_f32_e32 v167, v167, v182
	v_add_f32_e32 v167, v167, v184
	v_max3_f32 v169, v169, 0, v173
	v_max3_f32 v169, v169, v175, v177
	v_max3_f32 v172, v169, v181, v183
	v_mov_b32_e32 v169, v185
	v_add_f32_e32 v164, v167, v164
	v_fmamk_f32 v164, v164, 0x3a000000, v242
	v_cmp_gt_f32_e32 vcc, s4, v164
	v_mul_f32_e32 v167, 0x4f800000, v164
	v_max3_f32 v165, v172, v169, v165
	v_cndmask_b32_e32 v164, v164, v167, vcc
	v_sqrt_f32_e32 v167, v164
	s_nop 0
	v_add_u32_e32 v168, -1, v167
	v_fma_f32 v169, -v168, v167, v164
	v_cmp_ge_f32_e64 s[4:5], 0, v169
	v_add_u32_e32 v169, 1, v167
	s_nop 0
	v_cndmask_b32_e64 v168, v167, v168, s[4:5]
	v_fma_f32 v167, -v169, v167, v164
	v_cmp_lt_f32_e64 s[4:5], 0, v167
	s_nop 1
	v_cndmask_b32_e64 v167, v168, v169, s[4:5]
	v_mul_f32_e32 v168, 0x37800000, v167
	v_cndmask_b32_e32 v167, v167, v168, vcc
	v_cmp_class_f32_e32 vcc, v164, v243
	s_nop 1
	v_cndmask_b32_e32 v164, v167, v164, vcc
	v_div_scale_f32 v167, s[4:5], v164, v164, 1.0
	v_rcp_f32_e32 v168, v167
	s_nop 0
	v_fma_f32 v169, -v167, v168, 1.0
	v_fmac_f32_e32 v168, v169, v168
	v_div_scale_f32 v169, vcc, 1.0, v164, 1.0
	v_mul_f32_e32 v172, v169, v168
	v_fma_f32 v173, -v167, v172, v169
	v_fmac_f32_e32 v172, v173, v168
	v_fma_f32 v167, -v167, v172, v169
	v_div_fmas_f32 v167, v167, v168, v172
	v_div_fixup_f32 v164, v167, v164, 1.0
	v_lshl_add_u32 v167, v236, 3, 0
	ds_write_b64 v167, v[164:165] offset:8192
